# A attention: next tile's score-accumulator initialisation (ALiBi bias) computed at the end of the current tile, before the barrier, instead of after it in front of the first QK MFMA
# baseline (speedup 1.0000x reference)
; __device__ __forceinline__ int tid_fresh(int wave) { return wave * 64 + lane_id_fresh(); }
; #define LAS __attribute__((address_space(3)))
; #define LOADA(tt) do { const char* kp_ = kgp + (size_t)(tt) * tstep; const char* vp_ = vgp + (size_t)(tt) * tstep; ka0 = *(const u32x4*)kp_; ka1 = *(const u32x4*)(kp_ + 16); va0 = *(const u32x4*)vp_; va1 = *(const u32x4*)(vp_ + 16); } while (0)
; #define LOADB(tt) do { const char* kp_ = kgp + (size_t)(tt) * tstep; const char* vp_ = vgp + (size_t)(tt) * tstep; kb0 = *(const u32x4*)kp_; kb1 = *(const u32x4*)(kp_ + 16); vb0 = *(const u32x4*)vp_; vb1 = *(const u32x4*)(vp_ + 16); } while (0)
; template <int NC>
; __device__ __forceinline__ void attn_shared_unit(LAS char* lds, bf16* qbase, const bf16* Kg, const bf16* Vg, int kvp, int nt, int qpos, int qw, float nslope, float negM0, float lam, const float* subln, int wave_id) {
;     const int wv = wave_id, tid = pg8::tid_fresh(wave_id);
;     const int lane = tid & 63, r32 = lane & 31, hi = lane >> 5;
;     const int cm = (NC == 2) ? (wv & 1) : 0;
;     constexpr int NQ = (NC == 2) ? 4 : 8;
;     bf16x8 Q[NQ];
;     { const bf16* qrow0 = qbase + (size_t)r32 * LDQ;
; #pragma unroll
;     for (int ks = 0; ks < NQ; ++ks) Q[ks] = *(const bf16x8*)(qrow0 + cm * 64 + 16 * ks + 8 * hi); }
;     f32x16 O[4]; float l = 0.f;
; #pragma unroll
;     for (int db = 0; db < 4; ++db) zero16(O[db]);
;     const int lrow = tid >> 3, lcb = (tid & 7) * 32;
;     const char* kgp = (const char*)(Kg + (size_t)lrow * kvp) + lcb; const char* vgp = (const char*)(Vg + (size_t)lrow * kvp) + lcb;
;     const size_t tstep = (size_t)64 * kvp * 2;
;     u32x4 ka0, ka1, va0, va1, kb0, kb1, vb0, vb1;
;     ...
;     constexpr int BUFB = 64 * KP + 64 * VP;
;     const float qd = (float)(qpos - 4 * hi);
;     const int td = qw >> 6;
;     if (NC == 2) {
;     const int qb0 = qw & ~127;
;     const float dkf = 152.f / fmaxf(-nslope, 1e-6f);
;     const int Dk = (dkf < 4096.f) ? (int)dkf + 1 : 4096;
;     int t_lo = ((qb0 - Dk > 0) ? (qb0 - Dk) : 0) >> 6, t_hi = ((qb0 + 127 + Dk) >> 6) + 1;
;     t_lo &= ~1; t_hi = (t_hi + 1) & ~1; if (t_hi > nt) t_hi = nt;
;     LOADA(t_lo); LOADB(t_lo + 1);
;     __syncthreads();
;     WRITEA(0);
;     __syncthreads();
.LBB0_269:
	s_andn2_b64 vcc, exec, s[4:5]
	s_cbranch_vccnz .LBB0_262
	s_lshl_b32 s26, s86, 7
	s_ashr_i32 s57, s56, 31
	s_add_i32 s87, s26, s65
	s_lshl_b64 s[4:5], s[56:57], 11
	s_ashr_i32 s27, s26, 31
	s_add_u32 s26, s26, s65
	s_addc_u32 s27, s27, 0
	s_add_u32 s4, s26, s4
	s_addc_u32 s5, s27, s5
	s_mulk_i32 s5, 0x3400
	s_mul_hi_u32 s26, s4, 0x3400
	s_add_i32 s26, s26, s5
	s_mulk_i32 s4, 0x3400
	s_add_u32 s27, s18, s4
	s_addc_u32 s26, s19, s26
	s_lshl_b32 s4, s84, 7
	s_ashr_i32 s5, s4, 31
	s_lshl_b64 s[4:5], s[4:5], 1
	s_add_u32 s58, s27, s4
	s_addc_u32 s59, s26, s5
	s_mul_i32 s27, s56, 0x1a00000
	s_mul_hi_i32 s26, s56, 0x1a00000
	s_add_u32 s57, s18, s27
	s_addc_u32 s60, s19, s26
	s_add_u32 s78, s57, s4
	s_addc_u32 s79, s60, s5
	s_add_i32 s57, s84, 1
	v_cvt_f32_i32_e32 v0, s57
	s_mov_b32 s60, 0
	s_mov_b32 s57, 0
	v_mul_f32_e32 v0, -2.0, v0
	v_exp_f32_e32 v0, v0
	s_mov_b32 s61, 0x45800000
	v_mul_f32_e32 v225, 0xbfb8aa3b, v0
	v_mbcnt_lo_u32_b32 v0, -1, s57
	v_mbcnt_hi_u32_b32 v2, -1, v0
	v_and_b32_e32 v3, 31, v2
	v_mul_u32_u24_e32 v0, 0x1a00, v3
	v_lshlrev_b32_e32 v208, 1, v0
	v_lshlrev_b32_e32 v5, 5, v2
	s_mov_b32 s57, 0x358637bd
	v_lshl_add_u64 v[0:1], s[58:59], 0, v[208:209]
	v_and_b32_e32 v208, 0xe0, v5
	v_max_f32_e64 v5, -v225, s57
	v_div_scale_f32 v8, s[88:89], v5, v5, s71
	v_rcp_f32_e32 v9, v8
	v_bfe_u32 v4, v2, 5, 1
	v_lshl_add_u64 v[6:7], v[0:1], 0, s[6:7]
	v_lshlrev_b32_e32 v0, 4, v4
	v_fma_f32 v10, -v8, v9, 1.0
	v_fmac_f32_e32 v9, v10, v9
	v_div_scale_f32 v10, vcc, s71, v5, s71
	v_mul_f32_e32 v11, v10, v9
	v_fma_f32 v12, -v8, v11, v10
	v_fmac_f32_e32 v11, v12, v9
	v_fma_f32 v8, -v8, v11, v10
	v_div_fmas_f32 v8, v8, v9, v11
	v_div_fixup_f32 v5, v8, v5, s71
	v_cvt_i32_f32_e32 v8, v5
	v_mov_b32_e32 v1, v209
	v_lshl_add_u64 v[6:7], v[6:7], 0, v[0:1]
	v_add_u32_e32 v1, s80, v2
	v_cmp_gt_f32_e32 vcc, s61, v5
	v_readfirstlane_b32 s61, v8
	global_load_dwordx4 v[162:165], v[6:7], off
	global_load_dwordx4 v[166:169], v[6:7], off offset:32
	global_load_dwordx4 v[170:173], v[6:7], off offset:64
	global_load_dwordx4 v[174:177], v[6:7], off offset:96
	v_ashrrev_i32_e32 v1, 3, v1
	v_mov_b64_e32 v[6:7], s[78:79]
	s_and_b32 s57, s87, 0xffffff80
	s_add_i32 s61, s61, 1
	v_mad_i64_i32 v[6:7], s[78:79], v1, s70, v[6:7]
	s_and_b64 s[78:79], vcc, exec
	s_cselect_b32 s78, s61, 0x1000
	s_sub_i32 s57, s57, s78
	s_max_i32 s61, s57, 0
	s_or_b32 s57, s87, 0x7f
	s_add_i32 s78, s78, s57
	s_ashr_i32 s57, s78, 6
	s_lshr_b32 s79, s61, 6
	s_and_b32 s57, s57, -2
	s_and_b32 s78, s79, 0x1fffffe
	s_add_i32 s85, s57, 2
	s_cmp_lt_i32 s57, 32
	v_lshl_add_u64 v[6:7], v[6:7], 0, v[208:209]
	s_cselect_b32 s57, s85, 32
	s_or_b32 s79, s79, 1
	v_mad_u64_u32 v[8:9], s[88:89], s78, v138, v[6:7]
	v_mad_u64_u32 v[6:7], s[88:89], s79, v138, v[6:7]
	global_load_dwordx4 v[190:193], v[8:9], off offset:1040
	global_load_dwordx4 v[178:181], v[8:9], off offset:1024
	global_load_dwordx4 v[202:205], v[8:9], off offset:2064
	global_load_dwordx4 v[194:197], v[8:9], off offset:2048
	global_load_dwordx4 v[182:185], v[6:7], off offset:1040
	global_load_dwordx4 v[186:189], v[6:7], off offset:1024
	global_load_dwordx4 v[198:201], v[6:7], off offset:2064
	global_load_dwordx4 v[210:213], v[6:7], off offset:2048
	v_mul_lo_u32 v5, v1, s72
	v_add_u32_e32 v252, 0, v5
	v_mad_u64_u32 v[228:229], s[88:89], v1, 48, v[252:253]
	v_add_u32_e32 v5, v252, v208
	s_cmp_ge_i32 s78, s57
	v_add_u32_e32 v6, v228, v208
	s_waitcnt lgkmcnt(0)
	s_barrier
	s_waitcnt vmcnt(6)
	ds_write_b128 v5, v[178:181]
	ds_write_b128 v5, v[190:193] offset:16
	s_waitcnt vmcnt(4)
	ds_write_b128 v6, v[194:197] offset:17408
	ds_write_b128 v6, v[202:205] offset:17424
	s_waitcnt lgkmcnt(0)
	s_barrier
	s_cbranch_scc1 .LBB0_287
; template <int NC, bool DIAG>
; __device__ __forceinline__ void attn_tile(f32x16 (&O)[4], float& l, const bf16x8* Q, const LAS char* Kb, const LAS char* Vb, int r32, int hi, int lane, float qd, int k0, int qw, float nslope, float negM0) {
;     ...
;     const int k1 = k0 + 32;
;     if (NC == 2) {
;         const float ns0 = (k0 < qw) ? nslope : ((k0 > qw) ? -nslope : 0.f), ns1 = (k1 < qw) ? nslope : ((k1 > qw) ? -nslope : 0.f);
;         const float b0 = fmaf(ns0, qd - (float)k0, negM0), b1 = fmaf(ns1, qd - (float)k1, negM0);
; #pragma unroll
;         for (int r = 0; r < 16; ++r) { S0[r] = fmaf(-ns0, (float)((r & 3) + 8 * (r >> 2)), b0); S1[r] = fmaf(-ns1, (float)((r & 3) + 8 * (r >> 2)), b1); }
; template <int NC>
; __device__ __forceinline__ void attn_shared_unit(LAS char* lds, bf16* qbase, const bf16* Kg, const bf16* Vg, int kvp, int nt, int qpos, int qw, float nslope, float negM0, float lam, const float* subln, int wave_id) {
;     ...
;     f32x16 O[4]; float l = 0.f;
; #pragma unroll
;     for (int db = 0; db < 4; ++db) zero16(O[db]);
;     const int lrow = tid >> 3, lcb = (tid & 7) * 32;
;     const char* kgp = (const char*)(Kg + (size_t)lrow * kvp) + lcb; const char* vgp = (const char*)(Vg + (size_t)lrow * kvp) + lcb;
;     const size_t tstep = (size_t)64 * kvp * 2;
;     u32x4 ka0, ka1, va0, va1, kb0, kb1, vb0, vb1;
;     ...
;     constexpr int BUFB = 64 * KP + 64 * VP;
;     const float qd = (float)(qpos - 4 * hi);
;     const int td = qw >> 6;
;     if (NC == 2) {
;     const int qb0 = qw & ~127;
;     const float dkf = 152.f / fmaxf(-nslope, 1e-6f);
;     const int Dk = (dkf < 4096.f) ? (int)dkf + 1 : 4096;
;     int t_lo = ((qb0 - Dk > 0) ? (qb0 - Dk) : 0) >> 6, t_hi = ((qb0 + 127 + Dk) >> 6) + 1;
;     t_lo &= ~1; t_hi = (t_hi + 1) & ~1; if (t_hi > nt) t_hi = nt;
	v_mbcnt_lo_u32_b32 v5, -1, s60
	v_mbcnt_hi_u32_b32 v5, -1, v5
	v_and_or_b32 v5, v5, 31, s87
	v_lshlrev_b32_e32 v4, 2, v4
	v_sub_u32_e32 v4, v5, v4
	v_and_b32_e32 v6, 63, v2
	v_cvt_f32_i32_e32 v219, v4
	s_ashr_i32 s60, s87, 6
	v_mov_b32_e32 v4, s66
	v_mad_u32_u24 v4, v3, s72, v4
	v_bfe_u32 v3, v2, 2, 2
	v_and_b32_e32 v5, 16, v2
	v_lshrrev_b32_e32 v2, 3, v2
	v_lshlrev_b32_e32 v6, 2, v6
	s_sub_i32 s85, 0, s60
	s_lshr_b32 s60, s61, 7
	s_and_b32 s61, s61, 0x7fffff80
	v_and_or_b32 v2, v2, 4, v3
	v_and_or_b32 v5, v6, 12, v5
	s_add_i32 s88, s78, 3
	s_or_b32 s89, s61, 64
	s_mul_hi_u32 s61, s60, 0x1a0000
	s_mul_i32 s60, s60, 0x1a0000
	v_mul_u32_u24_e32 v3, 0x140, v2
	v_lshlrev_b32_e32 v5, 1, v5
	s_add_u32 s60, s27, s60
	v_add3_u32 v226, 0, v3, v5
	v_mov_b32_e32 v3, s73
	s_movk_i32 s79, 0x140
	s_addc_u32 s61, s26, s61
	v_mad_u32_u24 v6, v2, s79, v3
	v_mov_b64_e32 v[2:3], s[60:61]
	v_mad_i64_i32 v[2:3], s[26:27], v1, s70, v[2:3]
	s_add_u32 s4, s68, s4
	v_lshl_add_u64 v[2:3], v[2:3], 0, v[208:209]
	s_addc_u32 s5, s69, s5
	v_mov_b32_e32 v229, 0
	v_lshl_add_u64 v[216:217], s[4:5], 0, v[2:3]
	v_add_u32_e32 v227, v4, v0
	v_add_u32_e32 v221, v6, v5
	v_mov_b32_e32 v0, 0
	v_mov_b32_e32 v1, v229
	v_mov_b32_e32 v2, v229
	v_mov_b32_e32 v3, v229
	v_mov_b32_e32 v4, v229
	v_mov_b32_e32 v5, v229
	v_mov_b32_e32 v6, v229
	v_mov_b32_e32 v7, v229
	v_mov_b32_e32 v8, v229
	v_mov_b32_e32 v9, v229
	v_mov_b32_e32 v10, v229
	v_mov_b32_e32 v11, v229
	v_mov_b32_e32 v12, v229
	v_mov_b32_e32 v13, v229
	v_mov_b32_e32 v14, v229
	v_mov_b32_e32 v15, v229
	v_mov_b32_e32 v16, 0
	v_mov_b32_e32 v17, v229
	v_mov_b32_e32 v18, v229
	v_mov_b32_e32 v19, v229
	v_mov_b32_e32 v20, v229
	v_mov_b32_e32 v21, v229
	v_mov_b32_e32 v22, v229
	v_mov_b32_e32 v23, v229
	v_mov_b32_e32 v24, v229
	v_mov_b32_e32 v25, v229
	v_mov_b32_e32 v26, v229
	v_mov_b32_e32 v27, v229
	v_mov_b32_e32 v28, v229
	v_mov_b32_e32 v29, v229
	v_mov_b32_e32 v30, v229
	v_mov_b32_e32 v31, v229
	v_mov_b32_e32 v32, 0
	v_mov_b32_e32 v33, v229
	v_mov_b32_e32 v34, v229
	v_mov_b32_e32 v35, v229
	v_mov_b32_e32 v36, v229
	v_mov_b32_e32 v37, v229
	v_mov_b32_e32 v38, v229
	v_mov_b32_e32 v39, v229
	v_mov_b32_e32 v40, v229
	v_mov_b32_e32 v41, v229
	v_mov_b32_e32 v42, v229
	v_mov_b32_e32 v43, v229
	v_mov_b32_e32 v44, v229
	v_mov_b32_e32 v45, v229
	v_mov_b32_e32 v46, v229
	v_mov_b32_e32 v47, v229
	v_mov_b32_e32 v48, 0
	v_mov_b32_e32 v49, v229
	v_mov_b32_e32 v50, v229
	v_mov_b32_e32 v51, v229
	v_mov_b32_e32 v52, v229
	v_mov_b32_e32 v53, v229
	v_mov_b32_e32 v54, v229
	v_mov_b32_e32 v55, v229
	v_mov_b32_e32 v56, v229
	v_mov_b32_e32 v57, v229
	v_mov_b32_e32 v58, v229
	v_mov_b32_e32 v59, v229
	v_mov_b32_e32 v60, v229
	v_mov_b32_e32 v61, v229
	v_mov_b32_e32 v62, v229
	v_mov_b32_e32 v63, v229
	s_sub_i32 s27, s89, 64
	s_add_i32 s26, s27, 32
	s_cmp_lt_i32 s27, s87
	s_cselect_b64 vcc, -1, 0
	s_cmp_gt_i32 s27, s87
	s_cselect_b64 s[78:79], -1, 0
	v_cndmask_b32_e64 v64, 0, -v225, s[78:79]
	s_cmp_lt_i32 s26, s87
	v_cndmask_b32_e32 v218, v64, v225, vcc
	v_cvt_f32_i32_e32 v64, s27
	v_cvt_f32_i32_e32 v66, s26
	s_cselect_b64 s[4:5], -1, 0
	s_cmp_gt_i32 s26, s87
	s_cselect_b64 s[92:93], -1, 0
	v_cndmask_b32_e64 v65, 0, -v225, s[92:93]
	v_cndmask_b32_e64 v220, v65, v225, s[4:5]
	v_sub_f32_e32 v231, v219, v64
	v_sub_f32_e32 v230, v219, v66
	v_fma_f32 v222, v218, v231, v254
	v_fma_f32 v224, v220, v230, v254
	v_fmamk_f32 v144, v218, 0x80000000, v222
	v_fmamk_f32 v128, v220, 0x80000000, v224
	v_sub_f32_e32 v145, v222, v218
	v_sub_f32_e32 v129, v224, v220
	s_add_i32 s91, s85, s88
	s_cmp_lg_u32 s91, 3
	s_cbranch_scc0 .Lmy_sinit_p
	v_pk_fma_f32 v[146:147], v[218:219], s[22:23], v[222:223] op_sel_hi:[0,1,0] neg_lo:[1,0,0] neg_hi:[1,0,0]
	v_pk_fma_f32 v[130:131], v[220:221], s[22:23], v[224:225] op_sel_hi:[0,1,0] neg_lo:[1,0,0] neg_hi:[1,0,0]
	v_pk_fma_f32 v[148:149], v[218:219], s[44:45], v[222:223] op_sel_hi:[0,1,0] neg_lo:[1,0,0] neg_hi:[1,0,0]
	v_pk_fma_f32 v[132:133], v[220:221], s[44:45], v[224:225] op_sel_hi:[0,1,0] neg_lo:[1,0,0] neg_hi:[1,0,0]
	v_pk_fma_f32 v[150:151], v[218:219], s[46:47], v[222:223] op_sel_hi:[0,1,0] neg_lo:[1,0,0] neg_hi:[1,0,0]
	v_pk_fma_f32 v[134:135], v[220:221], s[46:47], v[224:225] op_sel_hi:[0,1,0] neg_lo:[1,0,0] neg_hi:[1,0,0]
	v_pk_fma_f32 v[152:153], v[218:219], s[48:49], v[222:223] op_sel_hi:[0,1,0] neg_lo:[1,0,0] neg_hi:[1,0,0]
	v_pk_fma_f32 v[136:137], v[220:221], s[48:49], v[224:225] op_sel_hi:[0,1,0] neg_lo:[1,0,0] neg_hi:[1,0,0]
	v_pk_fma_f32 v[154:155], v[218:219], s[50:51], v[222:223] op_sel_hi:[0,1,0] neg_lo:[1,0,0] neg_hi:[1,0,0]
	v_pk_fma_f32 v[138:139], v[220:221], s[50:51], v[224:225] op_sel_hi:[0,1,0] neg_lo:[1,0,0] neg_hi:[1,0,0]
	v_pk_fma_f32 v[156:157], v[218:219], s[52:53], v[222:223] op_sel_hi:[0,1,0] neg_lo:[1,0,0] neg_hi:[1,0,0]
	v_pk_fma_f32 v[140:141], v[220:221], s[52:53], v[224:225] op_sel_hi:[0,1,0] neg_lo:[1,0,0] neg_hi:[1,0,0]
	v_pk_fma_f32 v[158:159], v[218:219], s[54:55], v[222:223] op_sel_hi:[0,1,0] neg_lo:[1,0,0] neg_hi:[1,0,0]
	v_pk_fma_f32 v[142:143], v[220:221], s[54:55], v[224:225] op_sel_hi:[0,1,0] neg_lo:[1,0,0] neg_hi:[1,0,0]

; #define LAS __attribute__((address_space(3)))
; #define LOADA(tt) do { const char* kp_ = kgp + (size_t)(tt) * tstep; const char* vp_ = vgp + (size_t)(tt) * tstep; ka0 = *(const u32x4*)kp_; ka1 = *(const u32x4*)(kp_ + 16); va0 = *(const u32x4*)vp_; va1 = *(const u32x4*)(vp_ + 16); } while (0)
; template <int NC, bool DIAG>
; __device__ __forceinline__ void attn_tile(f32x16 (&O)[4], float& l, const bf16x8* Q, const LAS char* Kb, const LAS char* Vb, int r32, int hi, int lane, float qd, int k0, int qw, float nslope, float negM0) {
;     ...
;     const int k1 = k0 + 32;
;     if (NC == 2) {
;         const float ns0 = (k0 < qw) ? nslope : ((k0 > qw) ? -nslope : 0.f), ns1 = (k1 < qw) ? nslope : ((k1 > qw) ? -nslope : 0.f);
;         const float b0 = fmaf(ns0, qd - (float)k0, negM0), b1 = fmaf(ns1, qd - (float)k1, negM0);
; #pragma unroll
;         for (int r = 0; r < 16; ++r) { S0[r] = fmaf(-ns0, (float)((r & 3) + 8 * (r >> 2)), b0); S1[r] = fmaf(-ns1, (float)((r & 3) + 8 * (r >> 2)), b1); }
; template <int NC>
; __device__ __forceinline__ void attn_shared_unit(LAS char* lds, bf16* qbase, const bf16* Kg, const bf16* Vg, int kvp, int nt, int qpos, int qw, float nslope, float negM0, float lam, const float* subln, int wave_id) {
;     ...
;     for (int t = t_lo; t < t_hi; t += 2) {
;         {
;             if (t + 2 < t_hi) LOADA(t + 2);
;             int k0v = t * 64; asm volatile("" : "+s"(k0v));
;             const LAS char* Kb = lds + cm * 128; const LAS char* Vb = lds + 64 * KP;
;             if (t == td) attn_tile<NC, true>(O, l, Q, Kb, Vb, r32, hi, lane, qd, k0v, qw, nslope, negM0);
;             else attn_tile<NC, false>(O, l, Q, Kb, Vb, r32, hi, lane, qd, k0v, qw, nslope, negM0);
;             WRITEB(1);
;             __syncthreads();
;         }
;         {
;             if (t + 3 < t_hi) LOADB(t + 3);
;             int k0v = (t + 1) * 64; asm volatile("" : "+s"(k0v));
;             const LAS char* Kb = lds + BUFB + cm * 128; const LAS char* Vb = lds + BUFB + 64 * KP;
;             if (t + 1 == td) attn_tile<NC, true>(O, l, Q, Kb, Vb, r32, hi, lane, qd, k0v, qw, nslope, negM0);
;             else attn_tile<NC, false>(O, l, Q, Kb, Vb, r32, hi, lane, qd, k0v, qw, nslope, negM0);
;             if (t + 2 < t_hi) WRITEA(0);
;             __syncthreads();
;         }
.LBB0_272:
	s_add_i32 s88, s88, 2
	s_addk_i32 s89, 0x80
	s_sub_i32 s27, s89, 64
	s_add_i32 s26, s27, 32
	s_cmp_lt_i32 s27, s87
	s_cselect_b64 vcc, -1, 0
	s_cmp_gt_i32 s27, s87
	s_cselect_b64 s[78:79], -1, 0
	v_cndmask_b32_e64 v64, 0, -v225, s[78:79]
	s_cmp_lt_i32 s26, s87
	v_cndmask_b32_e32 v218, v64, v225, vcc
	v_cvt_f32_i32_e32 v64, s27
	v_cvt_f32_i32_e32 v66, s26
	s_cselect_b64 s[4:5], -1, 0
	s_cmp_gt_i32 s26, s87
	s_cselect_b64 s[92:93], -1, 0
	v_cndmask_b32_e64 v65, 0, -v225, s[92:93]
	v_cndmask_b32_e64 v220, v65, v225, s[4:5]
	v_sub_f32_e32 v231, v219, v64
	v_sub_f32_e32 v230, v219, v66
	v_fma_f32 v222, v218, v231, v254
	v_fma_f32 v224, v220, v230, v254
	v_fmamk_f32 v144, v218, 0x80000000, v222
	v_fmamk_f32 v128, v220, 0x80000000, v224
	v_sub_f32_e32 v145, v222, v218
	v_sub_f32_e32 v129, v224, v220
	s_add_i32 s91, s85, s88
	s_cmp_lg_u32 s91, 3
	s_cbranch_scc0 .Lmy_sinit_l
	v_pk_fma_f32 v[146:147], v[218:219], s[22:23], v[222:223] op_sel_hi:[0,1,0] neg_lo:[1,0,0] neg_hi:[1,0,0]
	v_pk_fma_f32 v[130:131], v[220:221], s[22:23], v[224:225] op_sel_hi:[0,1,0] neg_lo:[1,0,0] neg_hi:[1,0,0]
	v_pk_fma_f32 v[148:149], v[218:219], s[44:45], v[222:223] op_sel_hi:[0,1,0] neg_lo:[1,0,0] neg_hi:[1,0,0]
	v_pk_fma_f32 v[132:133], v[220:221], s[44:45], v[224:225] op_sel_hi:[0,1,0] neg_lo:[1,0,0] neg_hi:[1,0,0]
	v_pk_fma_f32 v[150:151], v[218:219], s[46:47], v[222:223] op_sel_hi:[0,1,0] neg_lo:[1,0,0] neg_hi:[1,0,0]
	v_pk_fma_f32 v[134:135], v[220:221], s[46:47], v[224:225] op_sel_hi:[0,1,0] neg_lo:[1,0,0] neg_hi:[1,0,0]
	v_pk_fma_f32 v[152:153], v[218:219], s[48:49], v[222:223] op_sel_hi:[0,1,0] neg_lo:[1,0,0] neg_hi:[1,0,0]
	v_pk_fma_f32 v[136:137], v[220:221], s[48:49], v[224:225] op_sel_hi:[0,1,0] neg_lo:[1,0,0] neg_hi:[1,0,0]
	v_pk_fma_f32 v[154:155], v[218:219], s[50:51], v[222:223] op_sel_hi:[0,1,0] neg_lo:[1,0,0] neg_hi:[1,0,0]
	v_pk_fma_f32 v[138:139], v[220:221], s[50:51], v[224:225] op_sel_hi:[0,1,0] neg_lo:[1,0,0] neg_hi:[1,0,0]
	v_pk_fma_f32 v[156:157], v[218:219], s[52:53], v[222:223] op_sel_hi:[0,1,0] neg_lo:[1,0,0] neg_hi:[1,0,0]
	v_pk_fma_f32 v[140:141], v[220:221], s[52:53], v[224:225] op_sel_hi:[0,1,0] neg_lo:[1,0,0] neg_hi:[1,0,0]
	v_pk_fma_f32 v[158:159], v[218:219], s[54:55], v[222:223] op_sel_hi:[0,1,0] neg_lo:[1,0,0] neg_hi:[1,0,0]
	v_pk_fma_f32 v[142:143], v[220:221], s[54:55], v[224:225] op_sel_hi:[0,1,0] neg_lo:[1,0,0] neg_hi:[1,0,0]
.Lmy_sinit_l:
	s_mov_b64 s[4:5], 0x1a0000
	s_cmp_ge_i32 s90, s57
	v_lshl_add_u64 v[216:217], v[216:217], 0, s[4:5]
	s_waitcnt lgkmcnt(0)
	s_barrier
	s_cbranch_scc1 .LBB0_288

; #define SCHED_FENCE() __builtin_amdgcn_sched_barrier(0)
; template <int NC, bool DIAG>
; __device__ __forceinline__ void attn_tile(f32x16 (&O)[4], float& l, const bf16x8* Q, const LAS char* Kb, const LAS char* Vb, int r32, int hi, int lane, float qd, int k0, int qw, float nslope, float negM0) {
;     ...
;     if (NC == 2) {
;         bf16x8 kf0[NQ], kf1[NQ];
;         kload32<NQ>(kf0, Kb, r32, hi);
;         SCHED_FENCE();
;         qkmm32<NQ>(S0, kf0, Q);
;         kload32<NQ>(kf1, Kb + 32 * KP, r32, hi);
;         vload16<0>(vf0, Vb, lane);
;         SCHED_FENCE();
;         qkmm32<NQ>(S1, kf1, Q);
;         if (DIAG) { const float nd = (k0 == qw) ? nslope : 0.f;
; #pragma unroll
;             for (int r = 0; r < 16; ++r) S0[r] = fmaf(nd, fabsf(qd - (float)k0 - (float)((r & 3) + 8 * (r >> 2))), S0[r]); }
;         soft32<0>(S0, P0, l, 0.f, 0.f);
;         vload16<1>(vf0, Vb, lane);
;         SCHED_FENCE();
;     } else {
;         bf16x8 kf[NQ];
;         kload32<NQ>(kf, Kb, r32, hi);
;         SCHED_FENCE();
;         qkmm32<NQ>(S0, kf, Q);
;         kload32<NQ>(kf, Kb + 32 * KP, r32, hi);
;         vload32(vf0, Vb, lane);
;         SCHED_FENCE();
;         qkmm32<NQ>(S1, kf, Q);
;         soft32<0>(S0, P0, l, 0.f, 0.f);
;         SCHED_FENCE();
;     }
;     pvmm32(O, P0, vf0);
;     if (NC == 2 && DIAG) { const float nd = (k1 == qw) ? nslope : 0.f;
; #pragma unroll
;         for (int r = 0; r < 16; ++r) S1[r] = fmaf(nd, fabsf(qd - (float)k1 - (float)((r & 3) + 8 * (r >> 2))), S1[r]); }
;     soft32<0>(S1, P1, l, 0.f, 0.f);
;     if (NC == 2) {
;     vload16<0>(vf1, Vb + 32 * VP, lane);
;     SCHED_FENCE();
;     vload16<1>(vf1, Vb + 32 * VP, lane);
;     } else {
;     vload32(vf1, Vb + 32 * VP, lane);
;     SCHED_FENCE();
;     }
;     pvmm32(O, P1, vf1);
.LBB0_275:
	s_add_i32 s91, s85, s88
	s_cmp_lg_u32 s91, 3
	s_mov_b64 s[4:5], -1
	s_cbranch_scc0 .LBB0_277
	s_waitcnt lgkmcnt(3)
	s_nop 0
	v_mfma_f32_32x32x16_bf16 v[64:79], v[80:83], v[162:165], v[144:159]
	s_waitcnt lgkmcnt(2)
	v_mfma_f32_32x32x16_bf16 v[64:79], v[84:87], v[166:169], v[64:79]
	s_waitcnt lgkmcnt(1)
	v_mfma_f32_32x32x16_bf16 v[64:79], v[88:91], v[170:173], v[64:79]
	s_waitcnt lgkmcnt(0)
	v_mfma_f32_32x32x16_bf16 v[64:79], v[92:95], v[174:177], v[64:79]
	ds_read_b128 v[80:83], v227 offset:8704
	ds_read_b128 v[84:87], v227 offset:8736
	ds_read_b128 v[88:91], v227 offset:8768
	ds_read_b128 v[92:95], v227 offset:8800
	ds_read_b64_tr_b16 v[96:97], v226 offset:17408
	ds_read_b64_tr_b16 v[98:99], v226 offset:19968
	ds_read_b64_tr_b16 v[100:101], v226 offset:17472
	ds_read_b64_tr_b16 v[102:103], v226 offset:20032
	ds_read_b64_tr_b16 v[112:113], v226 offset:17536
	ds_read_b64_tr_b16 v[114:115], v226 offset:20096
	ds_read_b64_tr_b16 v[232:233], v226 offset:17600
	ds_read_b64_tr_b16 v[234:235], v226 offset:20160
	v_exp_f32_e32 v64, v64
	v_exp_f32_e32 v65, v65
	s_waitcnt lgkmcnt(11)
	v_mfma_f32_32x32x16_bf16 v[146:161], v[80:83], v[162:165], v[128:143]
	v_exp_f32_e32 v66, v66
	v_exp_f32_e32 v67, v67
	v_add_f32_e32 v104, v229, v64
	v_exp_f32_e32 v68, v68
	v_add_f32_e32 v80, v65, v104
	v_exp_f32_e32 v69, v69
	v_add_f32_e32 v80, v66, v80
	s_waitcnt lgkmcnt(10)
	v_mfma_f32_32x32x16_bf16 v[146:161], v[84:87], v[166:169], v[146:161]
	v_exp_f32_e32 v70, v70
	v_add_f32_e32 v80, v67, v80
	v_exp_f32_e32 v71, v71
	v_add_f32_e32 v80, v68, v80
	v_exp_f32_e32 v72, v72
	v_add_f32_e32 v80, v69, v80
	v_exp_f32_e32 v73, v73
	ds_read_b64_tr_b16 v[134:135], v226 offset:22528
	ds_read_b64_tr_b16 v[138:139], v226 offset:22592
	ds_read_b64_tr_b16 v[236:237], v226 offset:22656
	ds_read_b64_tr_b16 v[240:241], v226 offset:22720
	ds_read_b64_tr_b16 v[136:137], v226 offset:25088
	ds_read_b64_tr_b16 v[140:141], v226 offset:25152
	ds_read_b64_tr_b16 v[238:239], v226 offset:25216
	ds_read_b64_tr_b16 v[242:243], v226 offset:25280
	v_add_f32_e32 v80, v70, v80
	v_exp_f32_e32 v74, v74
	v_add_f32_e32 v80, v71, v80
	v_exp_f32_e32 v75, v75
	s_waitcnt lgkmcnt(14)
	v_mfma_f32_32x32x16_bf16 v[146:161], v[88:91], v[170:173], v[146:161]
	v_add_f32_e32 v80, v72, v80
	v_exp_f32_e32 v76, v76
	v_add_f32_e32 v80, v73, v80
	v_exp_f32_e32 v77, v77
	v_add_f32_e32 v80, v74, v80
	v_exp_f32_e32 v78, v78
	v_add_f32_e32 v80, v75, v80
	v_exp_f32_e32 v79, v79
	v_add_f32_e32 v80, v76, v80
	v_add_f32_e32 v80, v77, v80
	v_add_f32_e32 v80, v78, v80
	v_add_f32_e32 v80, v79, v80
	v_mfma_f32_32x32x16_bf16 v[146:161], v[92:95], v[174:177], v[146:161]
	v_cvt_pk_bf16_f32 v130, v64, v65
	v_cvt_pk_bf16_f32 v131, v66, v67
	v_cvt_pk_bf16_f32 v132, v68, v69
	v_cvt_pk_bf16_f32 v133, v70, v71
	v_cvt_pk_bf16_f32 v244, v72, v73
	v_cvt_pk_bf16_f32 v245, v74, v75
	v_cvt_pk_bf16_f32 v246, v76, v77
	v_cvt_pk_bf16_f32 v247, v78, v79
	s_nop 3
	v_exp_f32_e32 v142, v146
	v_exp_f32_e32 v143, v147
	v_exp_f32_e32 v146, v148
	v_exp_f32_e32 v147, v149
	v_mfma_f32_32x32x16_bf16 v[64:79], v[96:99], v[130:133], v[48:63]
	v_add_f32_e32 v96, v80, v142
	v_exp_f32_e32 v148, v150
	v_add_f32_e32 v96, v143, v96
	v_exp_f32_e32 v149, v151
	v_add_f32_e32 v96, v146, v96
	v_exp_f32_e32 v150, v152
	v_add_f32_e32 v116, v147, v96
	v_exp_f32_e32 v151, v153
	s_waitcnt lgkmcnt(12)
	v_mfma_f32_32x32x16_bf16 v[80:95], v[100:103], v[130:133], v[32:47]
	v_exp_f32_e32 v153, v154
	v_exp_f32_e32 v154, v155
	v_exp_f32_e32 v155, v156
	v_exp_f32_e32 v156, v157
	v_exp_f32_e32 v157, v159
	s_waitcnt lgkmcnt(10)
	v_mfma_f32_32x32x16_bf16 v[96:111], v[112:115], v[130:133], v[16:31]
	v_add_f32_e32 v112, v148, v116
	v_add_f32_e32 v112, v149, v112
	v_add_f32_e32 v112, v150, v112
	v_add_f32_e32 v152, v151, v112
	s_waitcnt lgkmcnt(8)
	v_mfma_f32_32x32x16_bf16 v[112:127], v[232:235], v[130:133], v[0:15]
	v_add_f32_e32 v130, v153, v152
	v_exp_f32_e32 v152, v158
	v_add_f32_e32 v130, v154, v130
	v_add_f32_e32 v130, v155, v130
	v_add_f32_e32 v130, v156, v130
	v_add_f32_e32 v130, v152, v130
	v_add_f32_e32 v130, v157, v130
	s_waitcnt lgkmcnt(3)
	v_mfma_f32_32x32x16_bf16 v[64:79], v[134:137], v[244:247], v[64:79]
	v_cvt_pk_bf16_f32 v131, v146, v147
	v_cvt_pk_bf16_f32 v132, v148, v149
	v_cvt_pk_bf16_f32 v133, v150, v151
	v_cvt_pk_bf16_f32 v134, v153, v154
	v_cvt_pk_bf16_f32 v135, v155, v156
	v_cvt_pk_bf16_f32 v136, v152, v157
	v_exp_f32_e32 v137, v160
	s_waitcnt lgkmcnt(2)
	v_mfma_f32_32x32x16_bf16 v[80:95], v[138:141], v[244:247], v[80:95]
	ds_read_b64_tr_b16 v[138:139], v226 offset:27648
	ds_read_b64_tr_b16 v[146:147], v226 offset:27712
	ds_read_b64_tr_b16 v[150:151], v226 offset:27776
	ds_read_b64_tr_b16 v[154:155], v226 offset:27840
	ds_read_b64_tr_b16 v[140:141], v226 offset:30208
	ds_read_b64_tr_b16 v[148:149], v226 offset:30272
	ds_read_b64_tr_b16 v[152:153], v226 offset:30336
	ds_read_b64_tr_b16 v[156:157], v226 offset:30400
	v_exp_f32_e32 v158, v161
	v_add_f32_e32 v130, v137, v130
	v_add_f32_e32 v232, v158, v130
	v_cvt_pk_bf16_f32 v130, v142, v143
	s_waitcnt lgkmcnt(9)
	v_mfma_f32_32x32x16_bf16 v[96:111], v[236:239], v[244:247], v[96:111]
	v_cvt_pk_bf16_f32 v137, v137, v158
	s_waitcnt lgkmcnt(8)
	v_mfma_f32_32x32x16_bf16 v[112:127], v[240:243], v[244:247], v[112:127]
	s_waitcnt lgkmcnt(3)
	v_mfma_f32_32x32x16_bf16 v[64:79], v[138:141], v[130:133], v[64:79]
	ds_read_b64_tr_b16 v[140:141], v226 offset:35328
	s_mov_b64 s[4:5], 0
	s_waitcnt lgkmcnt(3)
	v_mfma_f32_32x32x16_bf16 v[80:95], v[146:149], v[130:133], v[80:95]
	s_waitcnt lgkmcnt(2)
	v_mfma_f32_32x32x16_bf16 v[96:111], v[150:153], v[130:133], v[96:111]
	s_waitcnt lgkmcnt(1)
	v_mfma_f32_32x32x16_bf16 v[112:127], v[154:157], v[130:133], v[112:127]
	ds_read_b64_tr_b16 v[138:139], v226 offset:32768
	ds_read_b64_tr_b16 v[130:131], v226 offset:32832
	ds_read_b64_tr_b16 v[146:147], v226 offset:32896
	ds_read_b64_tr_b16 v[150:151], v226 offset:32960
	ds_read_b64_tr_b16 v[132:133], v226 offset:35392
	ds_read_b64_tr_b16 v[148:149], v226 offset:35456
	ds_read_b64_tr_b16 v[152:153], v226 offset:35520
	s_waitcnt lgkmcnt(6)
	v_mfma_f32_32x32x16_bf16 v[64:79], v[138:141], v[134:137], v[64:79]
	s_waitcnt lgkmcnt(2)
	v_mfma_f32_32x32x16_bf16 v[80:95], v[130:133], v[134:137], v[80:95]
	s_waitcnt lgkmcnt(1)
	v_mfma_f32_32x32x16_bf16 v[96:111], v[146:149], v[134:137], v[96:111]
	s_waitcnt lgkmcnt(0)
	v_mfma_f32_32x32x16_bf16 v[112:127], v[150:153], v[134:137], v[112:127]

; #define LAS __attribute__((address_space(3)))
; #define LOADB(tt) do { const char* kp_ = kgp + (size_t)(tt) * tstep; const char* vp_ = vgp + (size_t)(tt) * tstep; kb0 = *(const u32x4*)kp_; kb1 = *(const u32x4*)(kp_ + 16); vb0 = *(const u32x4*)vp_; vb1 = *(const u32x4*)(vp_ + 16); } while (0)
; #define WRITEA(buf) do { LAS char* kw_ = lds + (buf) * BUFB + lrow * KP + lcb; LAS char* vw_ = lds + (buf) * BUFB + 64 * KP + lrow * VP + lcb; *(LAS u32x4*)kw_ = ka0; *(LAS u32x4*)(kw_ + 16) = ka1; *(LAS u32x4*)vw_ = va0; *(LAS u32x4*)(vw_ + 16) = va1; } while (0)
; #define WRITEB(buf) do { LAS char* kw_ = lds + (buf) * BUFB + lrow * KP + lcb; LAS char* vw_ = lds + (buf) * BUFB + 64 * KP + lrow * VP + lcb; *(LAS u32x4*)kw_ = kb0; *(LAS u32x4*)(kw_ + 16) = kb1; *(LAS u32x4*)vw_ = vb0; *(LAS u32x4*)(vw_ + 16) = vb1; } while (0)
; template <int NC, bool DIAG>
; __device__ __forceinline__ void attn_tile(f32x16 (&O)[4], float& l, const bf16x8* Q, const LAS char* Kb, const LAS char* Vb, int r32, int hi, int lane, float qd, int k0, int qw, float nslope, float negM0) {
;     ...
;     const int k1 = k0 + 32;
;     if (NC == 2) {
;         const float ns0 = (k0 < qw) ? nslope : ((k0 > qw) ? -nslope : 0.f), ns1 = (k1 < qw) ? nslope : ((k1 > qw) ? -nslope : 0.f);
;         const float b0 = fmaf(ns0, qd - (float)k0, negM0), b1 = fmaf(ns1, qd - (float)k1, negM0);
; #pragma unroll
;         for (int r = 0; r < 16; ++r) { S0[r] = fmaf(-ns0, (float)((r & 3) + 8 * (r >> 2)), b0); S1[r] = fmaf(-ns1, (float)((r & 3) + 8 * (r >> 2)), b1); }
; template <int NC>
; __device__ __forceinline__ void attn_shared_unit(LAS char* lds, bf16* qbase, const bf16* Kg, const bf16* Vg, int kvp, int nt, int qpos, int qw, float nslope, float negM0, float lam, const float* subln, int wave_id) {
;     ...
;             WRITEB(1);
;             __syncthreads();
;         }
;         {
;             if (t + 3 < t_hi) LOADB(t + 3);
;             int k0v = (t + 1) * 64; asm volatile("" : "+s"(k0v));
;             const LAS char* Kb = lds + BUFB + cm * 128; const LAS char* Vb = lds + BUFB + 64 * KP;
;             if (t + 1 == td) attn_tile<NC, true>(O, l, Q, Kb, Vb, r32, hi, lane, qd, k0v, qw, nslope, negM0);
;             else attn_tile<NC, false>(O, l, Q, Kb, Vb, r32, hi, lane, qd, k0v, qw, nslope, negM0);
;             if (t + 2 < t_hi) WRITEA(0);
;             __syncthreads();
.LBB0_279:
	v_add_u32_e32 v235, v252, v208
	v_add_u32_e32 v253, v228, v208
	s_cmp_ge_i32 s88, s57
	s_waitcnt vmcnt(2)
	ds_write_b128 v235, v[186:189] offset:37888
	ds_write_b128 v235, v[182:185] offset:37904
	s_waitcnt vmcnt(0)
	ds_write_b128 v253, v[210:213] offset:55296
	ds_write_b128 v253, v[198:201] offset:55312
	s_mov_b32 s26, s89
	s_add_i32 s78, s26, 32
	s_cmp_lt_i32 s26, s87
	s_cselect_b64 vcc, -1, 0
	s_cmp_gt_i32 s26, s87
	s_cselect_b64 s[4:5], -1, 0
	v_cndmask_b32_e64 v0, 0, -v225, s[4:5]
	s_cmp_lt_i32 s78, s87
	v_cndmask_b32_e32 v218, v0, v225, vcc
	v_cvt_f32_i32_e32 v0, s26
	v_cvt_f32_i32_e32 v2, s78
	s_cselect_b64 s[4:5], -1, 0
	s_cmp_gt_i32 s78, s87
	s_cselect_b64 s[92:93], -1, 0
	v_cndmask_b32_e64 v1, 0, -v225, s[92:93]
	v_cndmask_b32_e64 v220, v1, v225, s[4:5]
	v_sub_f32_e32 v234, v219, v0
	v_sub_f32_e32 v233, v219, v2
	v_fma_f32 v142, v218, v234, v254
	v_fma_f32 v224, v220, v233, v254
	v_fmamk_f32 v144, v218, 0x80000000, v142
	v_fmamk_f32 v128, v220, 0x80000000, v224
	v_sub_f32_e32 v145, v142, v218
	v_sub_f32_e32 v129, v224, v220
	s_cmp_lg_u32 s91, 2
	s_cbranch_scc0 .Lmy_sinit_o
	v_pk_fma_f32 v[146:147], v[218:219], s[22:23], v[142:143] op_sel_hi:[0,1,0] neg_lo:[1,0,0] neg_hi:[1,0,0]
	v_pk_fma_f32 v[148:149], v[218:219], s[44:45], v[142:143] op_sel_hi:[0,1,0] neg_lo:[1,0,0] neg_hi:[1,0,0]
	v_pk_fma_f32 v[150:151], v[218:219], s[46:47], v[142:143] op_sel_hi:[0,1,0] neg_lo:[1,0,0] neg_hi:[1,0,0]
	v_pk_fma_f32 v[152:153], v[218:219], s[48:49], v[142:143] op_sel_hi:[0,1,0] neg_lo:[1,0,0] neg_hi:[1,0,0]
	v_pk_fma_f32 v[154:155], v[218:219], s[50:51], v[142:143] op_sel_hi:[0,1,0] neg_lo:[1,0,0] neg_hi:[1,0,0]
	v_pk_fma_f32 v[156:157], v[218:219], s[52:53], v[142:143] op_sel_hi:[0,1,0] neg_lo:[1,0,0] neg_hi:[1,0,0]
	v_pk_fma_f32 v[158:159], v[218:219], s[54:55], v[142:143] op_sel_hi:[0,1,0] neg_lo:[1,0,0] neg_hi:[1,0,0]
	v_pk_fma_f32 v[142:143], v[220:221], s[54:55], v[224:225] op_sel_hi:[0,1,0] neg_lo:[1,0,0] neg_hi:[1,0,0]
	v_pk_fma_f32 v[130:131], v[220:221], s[22:23], v[224:225] op_sel_hi:[0,1,0] neg_lo:[1,0,0] neg_hi:[1,0,0]
	v_pk_fma_f32 v[132:133], v[220:221], s[44:45], v[224:225] op_sel_hi:[0,1,0] neg_lo:[1,0,0] neg_hi:[1,0,0]
	v_pk_fma_f32 v[134:135], v[220:221], s[46:47], v[224:225] op_sel_hi:[0,1,0] neg_lo:[1,0,0] neg_hi:[1,0,0]
	v_pk_fma_f32 v[136:137], v[220:221], s[48:49], v[224:225] op_sel_hi:[0,1,0] neg_lo:[1,0,0] neg_hi:[1,0,0]
	v_pk_fma_f32 v[138:139], v[220:221], s[50:51], v[224:225] op_sel_hi:[0,1,0] neg_lo:[1,0,0] neg_hi:[1,0,0]
	v_pk_fma_f32 v[140:141], v[220:221], s[52:53], v[224:225] op_sel_hi:[0,1,0] neg_lo:[1,0,0] neg_hi:[1,0,0]
.Lmy_sinit_o:
	s_waitcnt lgkmcnt(0)
	s_barrier
	s_cbranch_scc1 .LBB0_281
; #define SCHED_FENCE() __builtin_amdgcn_sched_barrier(0)
; #define LOADB(tt) do { const char* kp_ = kgp + (size_t)(tt) * tstep; const char* vp_ = vgp + (size_t)(tt) * tstep; kb0 = *(const u32x4*)kp_; kb1 = *(const u32x4*)(kp_ + 16); vb0 = *(const u32x4*)vp_; vb1 = *(const u32x4*)(vp_ + 16); } while (0)
; template <int NC, bool DIAG>
; __device__ __forceinline__ void attn_tile(f32x16 (&O)[4], float& l, const bf16x8* Q, const LAS char* Kb, const LAS char* Vb, int r32, int hi, int lane, float qd, int k0, int qw, float nslope, float negM0) {
;     ...
;     if (NC == 2) {
;         bf16x8 kf0[NQ], kf1[NQ];
;         kload32<NQ>(kf0, Kb, r32, hi);
;         SCHED_FENCE();
;         qkmm32<NQ>(S0, kf0, Q);
;         kload32<NQ>(kf1, Kb + 32 * KP, r32, hi);
;         vload16<0>(vf0, Vb, lane);
;         SCHED_FENCE();
;         qkmm32<NQ>(S1, kf1, Q);
;         if (DIAG) { const float nd = (k0 == qw) ? nslope : 0.f;
; #pragma unroll
;             for (int r = 0; r < 16; ++r) S0[r] = fmaf(nd, fabsf(qd - (float)k0 - (float)((r & 3) + 8 * (r >> 2))), S0[r]); }
;         soft32<0>(S0, P0, l, 0.f, 0.f);
;         vload16<1>(vf0, Vb, lane);
;         SCHED_FENCE();
;     } else {
;         bf16x8 kf[NQ];
;         kload32<NQ>(kf, Kb, r32, hi);
;         SCHED_FENCE();
;         qkmm32<NQ>(S0, kf, Q);
;         kload32<NQ>(kf, Kb + 32 * KP, r32, hi);
;         vload32(vf0, Vb, lane);
;         SCHED_FENCE();
;         qkmm32<NQ>(S1, kf, Q);
;         soft32<0>(S0, P0, l, 0.f, 0.f);
;         SCHED_FENCE();
;     }
;     pvmm32(O, P0, vf0);
;     if (NC == 2 && DIAG) { const float nd = (k1 == qw) ? nslope : 0.f;
; #pragma unroll
;         for (int r = 0; r < 16; ++r) S1[r] = fmaf(nd, fabsf(qd - (float)k1 - (float)((r & 3) + 8 * (r >> 2))), S1[r]); }
;     soft32<0>(S1, P1, l, 0.f, 0.f);
;     if (NC == 2) {
;     vload16<0>(vf1, Vb + 32 * VP, lane);
;     SCHED_FENCE();
;     vload16<1>(vf1, Vb + 32 * VP, lane);
;     } else {
;     vload32(vf1, Vb + 32 * VP, lane);
;     SCHED_FENCE();
;     }
;     pvmm32(O, P1, vf1);
; template <int NC>
; __device__ __forceinline__ void attn_shared_unit(LAS char* lds, bf16* qbase, const bf16* Kg, const bf16* Vg, int kvp, int nt, int qpos, int qw, float nslope, float negM0, float lam, const float* subln, int wave_id) {
;     ...
;             if (t + 3 < t_hi) LOADB(t + 3);
.LBB0_281:
	ds_read_b128 v[16:19], v227 offset:37888
	ds_read_b128 v[20:23], v227 offset:37920
	ds_read_b128 v[24:27], v227 offset:37952
	ds_read_b128 v[28:31], v227 offset:37984
	s_cmp_lg_u32 s91, 2
	s_mov_b64 s[4:5], -1
	s_cbranch_scc0 .LBB0_284
	s_waitcnt lgkmcnt(3)
	s_nop 0
	v_mfma_f32_32x32x16_bf16 v[0:15], v[16:19], v[162:165], v[144:159]
	s_waitcnt lgkmcnt(2)
	v_mfma_f32_32x32x16_bf16 v[0:15], v[20:23], v[166:169], v[0:15]
	ds_read_b128 v[16:19], v227 offset:46592
	ds_read_b128 v[20:23], v227 offset:46624
	ds_read_b128 v[32:35], v227 offset:46656
	ds_read_b128 v[36:39], v227 offset:46688
	s_waitcnt lgkmcnt(5)
	v_mfma_f32_32x32x16_bf16 v[0:15], v[24:27], v[170:173], v[0:15]
	ds_read_b64_tr_b16 v[24:25], v226 offset:55296
	ds_read_b64_tr_b16 v[236:237], v226 offset:55360
	ds_read_b64_tr_b16 v[240:241], v226 offset:55424
	ds_read_b64_tr_b16 v[244:245], v226 offset:55488
	ds_read_b64_tr_b16 v[26:27], v226 offset:57856
	ds_read_b64_tr_b16 v[238:239], v226 offset:57920
	ds_read_b64_tr_b16 v[242:243], v226 offset:57984
	ds_read_b64_tr_b16 v[246:247], v226 offset:58048
	s_waitcnt lgkmcnt(12)
	v_mfma_f32_32x32x16_bf16 v[0:15], v[28:31], v[174:177], v[0:15]
	s_nop 11
	v_exp_f32_e32 v0, v0
	v_exp_f32_e32 v1, v1
	s_waitcnt lgkmcnt(11)
	v_mfma_f32_32x32x16_bf16 v[146:161], v[16:19], v[162:165], v[128:143]
	v_exp_f32_e32 v2, v2
	v_exp_f32_e32 v3, v3
	v_add_f32_e32 v28, v232, v0
	v_exp_f32_e32 v4, v4
	v_add_f32_e32 v16, v1, v28
	v_exp_f32_e32 v5, v5
	v_add_f32_e32 v16, v2, v16
	s_waitcnt lgkmcnt(10)
	v_mfma_f32_32x32x16_bf16 v[146:161], v[20:23], v[166:169], v[146:161]
	v_exp_f32_e32 v6, v6
	v_add_f32_e32 v16, v3, v16
	v_exp_f32_e32 v7, v7
	v_add_f32_e32 v16, v4, v16
	v_exp_f32_e32 v8, v8
	s_waitcnt lgkmcnt(9)
	v_mfma_f32_32x32x16_bf16 v[146:161], v[32:35], v[170:173], v[146:161]
	v_add_f32_e32 v16, v5, v16
	v_exp_f32_e32 v9, v9
	v_add_f32_e32 v16, v6, v16
	v_exp_f32_e32 v10, v10
	v_add_f32_e32 v16, v7, v16
	v_exp_f32_e32 v11, v11
	v_add_f32_e32 v16, v8, v16
	v_exp_f32_e32 v12, v12
	ds_read_b64_tr_b16 v[134:135], v226 offset:60416
	ds_read_b64_tr_b16 v[138:139], v226 offset:60480
	ds_read_b64_tr_b16 v[248:249], v226 offset:60544
	ds_read_b64_tr_b16 v[182:183], v226 offset:60608
	ds_read_b64_tr_b16 v[136:137], v226 offset:62976
	ds_read_b64_tr_b16 v[140:141], v226 offset:63040
	ds_read_b64_tr_b16 v[250:251], v226 offset:63104
	ds_read_b64_tr_b16 v[184:185], v226 offset:63168
	v_add_f32_e32 v16, v9, v16
	v_exp_f32_e32 v13, v13
	s_waitcnt lgkmcnt(14)
	v_mfma_f32_32x32x16_bf16 v[146:161], v[36:39], v[174:177], v[146:161]
	v_add_f32_e32 v16, v10, v16
	v_exp_f32_e32 v14, v14
	v_add_f32_e32 v16, v11, v16
	v_exp_f32_e32 v15, v15
	v_add_f32_e32 v16, v12, v16
	v_add_f32_e32 v16, v13, v16
	v_add_f32_e32 v16, v14, v16
	v_add_f32_e32 v16, v15, v16
	v_cvt_pk_bf16_f32 v186, v8, v9
	v_cvt_pk_bf16_f32 v187, v10, v11
	v_cvt_pk_bf16_f32 v188, v12, v13
	v_cvt_pk_bf16_f32 v189, v14, v15
	v_cvt_pk_bf16_f32 v130, v0, v1
	v_cvt_pk_bf16_f32 v131, v2, v3
	v_cvt_pk_bf16_f32 v132, v4, v5
	v_cvt_pk_bf16_f32 v133, v6, v7
	v_exp_f32_e32 v142, v146
	v_exp_f32_e32 v143, v147
	v_exp_f32_e32 v146, v148
	v_exp_f32_e32 v147, v149
	v_add_f32_e32 v0, v16, v142
	v_exp_f32_e32 v148, v150
	v_add_f32_e32 v0, v143, v0
	v_exp_f32_e32 v149, v151
	v_add_f32_e32 v0, v146, v0
	v_exp_f32_e32 v150, v152
	v_add_f32_e32 v0, v147, v0
	v_exp_f32_e32 v151, v153
	v_add_f32_e32 v0, v148, v0
	v_exp_f32_e32 v153, v154
	s_waitcnt lgkmcnt(11)
	v_mfma_f32_32x32x16_bf16 v[48:63], v[24:27], v[130:133], v[64:79]
	v_add_f32_e32 v0, v149, v0
	v_exp_f32_e32 v154, v155
	v_add_f32_e32 v0, v150, v0
	v_exp_f32_e32 v155, v156
	v_add_f32_e32 v152, v151, v0
	v_exp_f32_e32 v156, v157
	v_exp_f32_e32 v157, v159
	s_waitcnt lgkmcnt(10)
	v_mfma_f32_32x32x16_bf16 v[32:47], v[236:239], v[130:133], v[80:95]
	s_waitcnt lgkmcnt(9)
	v_mfma_f32_32x32x16_bf16 v[16:31], v[240:243], v[130:133], v[96:111]
	s_waitcnt lgkmcnt(8)
	v_mfma_f32_32x32x16_bf16 v[0:15], v[244:247], v[130:133], v[112:127]
	v_add_f32_e32 v130, v153, v152
	v_exp_f32_e32 v152, v158
	v_add_f32_e32 v130, v154, v130
	v_add_f32_e32 v130, v155, v130
	v_add_f32_e32 v130, v156, v130
	v_add_f32_e32 v130, v152, v130
	v_add_f32_e32 v130, v157, v130
	s_waitcnt lgkmcnt(3)
	v_mfma_f32_32x32x16_bf16 v[48:63], v[134:137], v[186:189], v[48:63]
	v_cvt_pk_bf16_f32 v131, v146, v147
	v_cvt_pk_bf16_f32 v132, v148, v149
	v_cvt_pk_bf16_f32 v133, v150, v151
	v_cvt_pk_bf16_f32 v134, v153, v154
	v_cvt_pk_bf16_f32 v135, v155, v156
	v_cvt_pk_bf16_f32 v136, v152, v157
	v_exp_f32_e32 v137, v160
	s_waitcnt lgkmcnt(2)
	v_mfma_f32_32x32x16_bf16 v[32:47], v[138:141], v[186:189], v[32:47]
	ds_read_b64_tr_b16 v[138:139], v221
	ds_read_b64_tr_b16 v[146:147], v221 offset:64
	ds_read_b64_tr_b16 v[150:151], v221 offset:128
	ds_read_b64_tr_b16 v[154:155], v221 offset:192
	ds_read_b64_tr_b16 v[140:141], v221 offset:2560
	ds_read_b64_tr_b16 v[148:149], v221 offset:2624
	ds_read_b64_tr_b16 v[152:153], v221 offset:2688
	ds_read_b64_tr_b16 v[156:157], v221 offset:2752
	v_exp_f32_e32 v158, v161
	v_add_f32_e32 v130, v137, v130
	v_add_f32_e32 v229, v158, v130
	v_cvt_pk_bf16_f32 v130, v142, v143
	s_waitcnt lgkmcnt(9)
	v_mfma_f32_32x32x16_bf16 v[16:31], v[248:251], v[186:189], v[16:31]
	v_fma_f32 v142, v218, v234, v254
	v_cvt_pk_bf16_f32 v137, v137, v158
	s_waitcnt lgkmcnt(8)
	v_mfma_f32_32x32x16_bf16 v[0:15], v[182:185], v[186:189], v[0:15]
	s_waitcnt vmcnt(0)
	s_cmp_ge_i32 s88, s57
	s_cbranch_scc1 .Lmy_a_ldb_skip1
	global_load_dwordx4 v[182:185], v[216:217], off offset:-1024
	global_load_dwordx4 v[186:189], v[216:217], off offset:-1040
	global_load_dwordx4 v[198:201], v[216:217], off
	global_load_dwordx4 v[210:213], v[216:217], off offset:-16
